# v33: v32 + LDS operand prefetch for the M1 4-MFMA runs (both heads) and the RG-LRU 16-MFMA gate block (A fragments read ahead, counted waits)
# baseline (speedup 1.0000x reference)
; #define LAS __attribute__((address_space(3)))
; DI bf16_t f2bf(float f) { return (bf16_t)(cvt_pk(f, 0.f) & 0xffffu); }
; DI int crow(int reg, int h) { return (reg & 3) + 8 * (reg >> 2) + 4 * h; }
; DI void mma_blk_swz(f32x16& acc, const LAS bf16_t* A, const LAS bf16_t* Bsw, int r, int h, int rowB0) {
;     const int swz = ((rowB0 + r) >> 4) & 7;
; #pragma unroll
;     for (int ks = 0; ks < 4; ++ks) {
;         const bf16x8 av = *(const LAS bf16x8*)(A + r * 72 + ks * 16 + 8 * h);
;         const bf16x8 bv = *(const LAS bf16x8*)(Bsw + (rowB0 + r) * 72 + (((2 * ks + h) ^ swz) << 3));
;         acc = __builtin_amdgcn_mfma_f32_32x32x16_bf16(av, bv, acc, 0, 0, 0);
;     }
; }
; template <bool FINAL>
; DI void gla_unit(KA a, int l, int item, LAS unsigned char* lds) {
;     ...
;             mma_blk_swz(acc, ks + mb * 32 * 72, vT, r, h, nb * 32);
;             const int dvc = 32 * nb + r;
;             if (u.prompt) {
;                 bf16_t* dst = (bf16_t*)(a->ws + WS_SB) + (size_t)(unit * 4 + hd) * 8192;
; #pragma unroll
;                 for (int i = 0; i < 16; ++i) dst[(32 * mb + crow(i, h)) * 128 + dvc] = f2bf(acc[i]);
.LBB0_671:
	s_lshl_b32 s6, s47, 5
	s_and_b32 s6, s6, 0x60
	v_lshlrev_b32_e32 v49, 4, v96
	s_ashr_i32 s0, s48, 3
	v_or_b32_e32 v42, s6, v103
	s_movk_i32 s6, 0x70
	v_or_b32_e32 v0, 32, v49
	s_andn2_b32 s0, s0, 31
	v_bitop3_b32 v46, v42, v0, s6 bitop3:0x6c
	v_or_b32_e32 v0, 64, v49
	s_mul_i32 s5, s0, 0x90
	v_bitop3_b32 v47, v42, v49, s6 bitop3:0x6c
	v_bitop3_b32 v45, v42, v0, s6 bitop3:0x6c
	v_or_b32_e32 v0, 0x60, v49
	s_add_u32 s10, s28, 0xd200000
	v_mad_u32_u24 v25, v42, s27, 0
	s_waitcnt lgkmcnt(0)
	s_barrier
	v_mul_u32_u24_e32 v48, 0x90, v103
	v_bitop3_b32 v44, v42, v0, s6 bitop3:0x6c
	s_addc_u32 s11, s29, 0
	s_add_i32 s12, s5, 0
	v_add_u32_e32 v0, v25, v47
	v_add3_u32 v24, s12, v48, v49
	ds_read_b128 v[0:3], v0 offset:22528
	ds_read_b128 v[4:7], v24 offset:13312
	v_add_u32_e32 v20, v25, v46
	ds_read_b128 v[16:19], v24 offset:13344
	ds_read_b128 v[20:23], v20 offset:22528
	v_add_u32_e32 v110, v25, v45
	ds_read_b128 v[114:117], v24 offset:13376
	ds_read_b128 v[110:113], v110 offset:22528
	v_add_u32_e32 v118, v25, v44
	ds_read_b128 v[28:31], v24 offset:13408
	ds_read_b128 v[118:121], v118 offset:22528
	v_lshl_or_b32 v43, v96, 2, s0
	v_lshl_or_b32 v34, v43, 7, v42
	s_mov_b64 s[6:7], -1
	s_and_b64 vcc, exec, s[8:9]
	v_ashrrev_i32_e32 v35, 31, v34
	s_waitcnt lgkmcnt(6)
	v_mfma_f32_32x32x16_bf16 v[0:15], v[4:7], v[0:3], 0
	s_waitcnt lgkmcnt(4)
	v_mfma_f32_32x32x16_bf16 v[0:15], v[16:19], v[20:23], v[0:15]
	s_waitcnt lgkmcnt(2)
	v_mfma_f32_32x32x16_bf16 v[0:15], v[114:117], v[110:113], v[0:15]
	s_waitcnt lgkmcnt(0)
	v_mfma_f32_32x32x16_bf16 v[0:15], v[28:31], v[118:121], v[0:15]
	s_cbranch_vccnz .LBB0_673
	s_ashr_i32 s5, s4, 31
	s_lshl_b64 s[4:5], s[4:5], 14
	s_add_u32 s4, s10, s4
	s_addc_u32 s5, s11, s5
	v_cvt_pk_bf16_f32 v18, v0, v145
	v_lshl_add_u64 v[16:17], v[34:35], 1, s[4:5]
	global_store_short v[16:17], v18, off
	v_cvt_pk_bf16_f32 v18, v1, v145
	global_store_short v[16:17], v18, off offset:256
	v_cvt_pk_bf16_f32 v18, v2, v145
	global_store_short v[16:17], v18, off offset:512
	v_cvt_pk_bf16_f32 v18, v3, v145
	global_store_short v[16:17], v18, off offset:768
	v_cvt_pk_bf16_f32 v18, v4, v145
	global_store_short v[16:17], v18, off offset:2048
	v_cvt_pk_bf16_f32 v18, v5, v145
	global_store_short v[16:17], v18, off offset:2304
	v_cvt_pk_bf16_f32 v18, v6, v145
	s_movk_i32 s0, 0x1000
	global_store_short v[16:17], v18, off offset:2560
	v_cvt_pk_bf16_f32 v18, v7, v145
	global_store_short v[16:17], v18, off offset:2816
	v_add_co_u32_e32 v16, vcc, s0, v16
	v_cvt_pk_bf16_f32 v18, v8, v145
	s_mov_b64 s[6:7], 0
	s_nop 0
	v_addc_co_u32_e32 v17, vcc, 0, v17, vcc
	global_store_short v[16:17], v18, off
	v_cvt_pk_bf16_f32 v18, v9, v145
	global_store_short v[16:17], v18, off offset:256
	v_cvt_pk_bf16_f32 v18, v10, v145
	global_store_short v[16:17], v18, off offset:512
	v_cvt_pk_bf16_f32 v18, v11, v145
	global_store_short v[16:17], v18, off offset:768
	v_cvt_pk_bf16_f32 v18, v12, v145
	global_store_short v[16:17], v18, off offset:2048
	v_cvt_pk_bf16_f32 v18, v13, v145
	global_store_short v[16:17], v18, off offset:2304
	v_cvt_pk_bf16_f32 v18, v14, v145
	global_store_short v[16:17], v18, off offset:2560
	v_cvt_pk_bf16_f32 v18, v15, v145
	global_store_short v[16:17], v18, off offset:2816

; #define LAS __attribute__((address_space(3)))
; DI bf16_t f2bf(float f) { return (bf16_t)(cvt_pk(f, 0.f) & 0xffffu); }
; DI int crow(int reg, int h) { return (reg & 3) + 8 * (reg >> 2) + 4 * h; }
; DI void mma_blk_swz(f32x16& acc, const LAS bf16_t* A, const LAS bf16_t* Bsw, int r, int h, int rowB0) {
;     const int swz = ((rowB0 + r) >> 4) & 7;
; #pragma unroll
;     for (int ks = 0; ks < 4; ++ks) {
;         const bf16x8 av = *(const LAS bf16x8*)(A + r * 72 + ks * 16 + 8 * h);
;         const bf16x8 bv = *(const LAS bf16x8*)(Bsw + (rowB0 + r) * 72 + (((2 * ks + h) ^ swz) << 3));
;         acc = __builtin_amdgcn_mfma_f32_32x32x16_bf16(av, bv, acc, 0, 0, 0);
;     }
; }
; template <bool FINAL>
; DI void gla_unit(KA a, int l, int item, LAS unsigned char* lds) {
;     ...
;             mma_blk_swz(acc, ks + mb * 32 * 72, vT, r, h, nb * 32);
;             const int dvc = 32 * nb + r;
;             if (u.prompt) {
;                 bf16_t* dst = (bf16_t*)(a->ws + WS_SB) + (size_t)(unit * 4 + hd) * 8192;
; #pragma unroll
;                 for (int i = 0; i < 16; ++i) dst[(32 * mb + crow(i, h)) * 128 + dvc] = f2bf(acc[i]);
.LBB0_675:
	s_add_i32 s12, s12, 0x14000
	v_add3_u32 v17, s12, v48, v49
	v_mul_u32_u24_e32 v4, 0x90, v42
	v_readlane_b32 s0, v254, 47
	s_and_b64 vcc, exec, s[8:9]
	ds_read_b128 v[0:3], v17
	v_add_u32_e32 v19, s0, v4
	v_add_u32_e32 v4, v19, v47
	v_add_u32_e32 v21, v19, v46
	v_add_u32_e32 v122, v19, v45
	ds_read_b128 v[4:7], v4
	ds_read_b128 v[48:51], v17 offset:32
	ds_read_b128 v[52:55], v21
	ds_read_b128 v[110:113], v17 offset:64
	ds_read_b128 v[114:117], v122
	ds_read_b128 v[118:121], v17 offset:96
	v_add_u32_e32 v17, v19, v44
	ds_read_b128 v[44:47], v17
	s_mov_b64 s[4:5], -1
	s_waitcnt lgkmcnt(6)
	v_mfma_f32_32x32x16_bf16 v[0:15], v[0:3], v[4:7], 0
	s_waitcnt lgkmcnt(4)
	v_mfma_f32_32x32x16_bf16 v[0:15], v[48:51], v[52:55], v[0:15]
	s_waitcnt lgkmcnt(2)
	v_mfma_f32_32x32x16_bf16 v[0:15], v[110:113], v[114:117], v[0:15]
	s_waitcnt lgkmcnt(0)
	v_mfma_f32_32x32x16_bf16 v[0:15], v[118:121], v[44:47], v[0:15]
	s_cbranch_vccnz .LBB0_677
	s_or_b32 s4, s46, s26
	s_ashr_i32 s5, s4, 31
	s_lshl_b64 s[4:5], s[4:5], 14
	s_add_u32 s4, s10, s4
	s_addc_u32 s5, s11, s5
	v_cvt_pk_bf16_f32 v17, v0, v145
	v_lshl_add_u64 v[44:45], v[34:35], 1, s[4:5]
	global_store_short v[44:45], v17, off
	v_cvt_pk_bf16_f32 v17, v1, v145
	global_store_short v[44:45], v17, off offset:256
	v_cvt_pk_bf16_f32 v17, v2, v145
	global_store_short v[44:45], v17, off offset:512
	v_cvt_pk_bf16_f32 v17, v3, v145
	global_store_short v[44:45], v17, off offset:768
	v_cvt_pk_bf16_f32 v17, v4, v145
	global_store_short v[44:45], v17, off offset:2048
	v_cvt_pk_bf16_f32 v17, v5, v145
	global_store_short v[44:45], v17, off offset:2304
	v_cvt_pk_bf16_f32 v17, v6, v145
	s_movk_i32 s0, 0x1000
	global_store_short v[44:45], v17, off offset:2560
	v_cvt_pk_bf16_f32 v17, v7, v145
	global_store_short v[44:45], v17, off offset:2816
	v_add_co_u32_e32 v44, vcc, s0, v44
	v_cvt_pk_bf16_f32 v17, v8, v145
	s_mov_b64 s[4:5], 0
	s_nop 0
	v_addc_co_u32_e32 v45, vcc, 0, v45, vcc
	global_store_short v[44:45], v17, off
	v_cvt_pk_bf16_f32 v17, v9, v145
	global_store_short v[44:45], v17, off offset:256
	v_cvt_pk_bf16_f32 v17, v10, v145
	global_store_short v[44:45], v17, off offset:512
	v_cvt_pk_bf16_f32 v17, v11, v145
	global_store_short v[44:45], v17, off offset:768
	v_cvt_pk_bf16_f32 v17, v12, v145
	global_store_short v[44:45], v17, off offset:2048
	v_cvt_pk_bf16_f32 v17, v13, v145
	global_store_short v[44:45], v17, off offset:2304
	v_cvt_pk_bf16_f32 v17, v14, v145
	global_store_short v[44:45], v17, off offset:2560
	v_cvt_pk_bf16_f32 v17, v15, v145
	global_store_short v[44:45], v17, off offset:2816

; #define LAS __attribute__((address_space(3)))
; template <bool FINAL>
; DI void lru_unit(KA a, int l, int unit, LAS unsigned char* lds) {
;     ...
; #pragma unroll
;         for (int ks = 0; ks < 4; ++ks) {
;             const bf16x8 ba = fa[ks], bx = fx[ks];
; #pragma unroll
;             for (int mb = 0; mb < 2; ++mb) {
;                 const bf16x8 av = *(const LAS bf16x8*)(xc + (mb * 32 + taur) * 72 + ks * 16 + 8 * h);
;                 ar[mb] = __builtin_amdgcn_mfma_f32_32x32x16_bf16(av, ba, ar[mb], 0, 0, 0);
;                 ai[mb] = __builtin_amdgcn_mfma_f32_32x32x16_bf16(av, bx, ai[mb], 0, 0, 0);
;             }
;         }
;         if (nb == 0) {
; #pragma unroll
;             for (int ks = 0; ks < 4; ++ks) { fa[ks] = *(const bf16x8*)(WaT + (32 + r) * 64 + ks * 16 + 8 * h); fx[ks] = *(const bf16x8*)(WxT + (32 + r) * 64 + ks * 16 + 8 * h); }
.LBB0_1011:
	s_or_b64 exec, exec, s[4:5]
	ds_read_b128 v[200:203], v129
	ds_read_b128 v[204:207], v129 offset:32
	ds_read_b128 v[208:211], v129 offset:4608
	ds_read_b128 v[234:237], v129 offset:4640
	ds_read_b128 v[244:247], v129 offset:64
	ds_read_b128 v[248:251], v129 offset:4672
	ds_read_b128 v[180:183], v129 offset:96
	ds_read_b128 v[176:179], v129 offset:4704
	s_andn2_b64 vcc, exec, s[92:93]
	s_waitcnt vmcnt(7) lgkmcnt(7)
	v_mfma_f32_32x32x16_bf16 v[48:63], v[200:203], v[64:67], 0
	s_waitcnt vmcnt(6)
	v_mfma_f32_32x32x16_bf16 v[32:47], v[200:203], v[68:71], 0
	s_waitcnt vmcnt(5) lgkmcnt(6)
	v_mfma_f32_32x32x16_bf16 v[48:63], v[204:207], v[72:75], v[48:63]
	s_waitcnt vmcnt(4)
	v_mfma_f32_32x32x16_bf16 v[32:47], v[204:207], v[76:79], v[32:47]
	s_waitcnt lgkmcnt(5)
	v_mfma_f32_32x32x16_bf16 v[16:31], v[208:211], v[64:67], 0
	v_mfma_f32_32x32x16_bf16 v[0:15], v[208:211], v[68:71], 0
	s_waitcnt lgkmcnt(4)
	v_mfma_f32_32x32x16_bf16 v[16:31], v[234:237], v[72:75], v[16:31]
	v_mfma_f32_32x32x16_bf16 v[0:15], v[234:237], v[76:79], v[0:15]
	s_waitcnt vmcnt(3) lgkmcnt(3)
	v_mfma_f32_32x32x16_bf16 v[48:63], v[244:247], v[80:83], v[48:63]
	s_waitcnt vmcnt(2)
	v_mfma_f32_32x32x16_bf16 v[32:47], v[244:247], v[84:87], v[32:47]
	s_waitcnt lgkmcnt(2)
	v_mfma_f32_32x32x16_bf16 v[16:31], v[248:251], v[80:83], v[16:31]
	v_mfma_f32_32x32x16_bf16 v[0:15], v[248:251], v[84:87], v[0:15]
	s_waitcnt vmcnt(1) lgkmcnt(1)
	v_mfma_f32_32x32x16_bf16 v[48:63], v[180:183], v[88:91], v[48:63]
	s_waitcnt vmcnt(0)
	v_mfma_f32_32x32x16_bf16 v[32:47], v[180:183], v[92:95], v[32:47]
	s_waitcnt lgkmcnt(0)
	v_mfma_f32_32x32x16_bf16 v[16:31], v[176:179], v[88:91], v[16:31]
	v_mfma_f32_32x32x16_bf16 v[0:15], v[176:179], v[92:95], v[0:15]
	s_cbranch_vccnz .LBB0_1013
	global_load_dwordx4 v[64:67], v[114:115], off
	global_load_dwordx4 v[72:75], v[114:115], off offset:32
	global_load_dwordx4 v[68:71], v[116:117], off
	global_load_dwordx4 v[76:79], v[116:117], off offset:32
	global_load_dwordx4 v[80:83], v[114:115], off offset:64
	global_load_dwordx4 v[88:91], v[114:115], off offset:96
	global_load_dwordx4 v[84:87], v[116:117], off offset:64
	global_load_dwordx4 v[92:95], v[116:117], off offset:96
